# group seams 2/3: arrival atomic returns old count (sc0), skip poll when it shows last arriver (+neighbour load), on top of v52
# baseline (speedup 1.0000x reference)
.Lmy_s2_uni:
	s_and_b32 s8, s2, 63
	s_lshl_b32 s9, s8, 2
	s_add_i32 s9, s9, 14800
	v_mov_b32_e32 v0, s9
	v_mov_b32_e32 v1, 1
	global_atomic_add v1, v0, v1, s[52:53] sc0
	s_and_b32 s11, s8, 7
	s_lshr_b32 s14, s8, 3
	s_lshl_b32 s15, s11, 3
	s_add_i32 s15, s15, s14
	s_sub_i32 s15, s15, 1
	s_max_i32 s15, s15, 0
	s_lshr_b32 s11, s15, 3
	s_and_b32 s14, s15, 7
	s_lshl_b32 s14, s14, 3
	s_add_i32 s11, s11, s14
	s_lshl_b32 s11, s11, 2
	s_add_i32 s11, s11, 14800
	v_mov_b32_e32 v2, s11
	global_load_dword v3, v2, s[52:53] sc1
	s_waitcnt vmcnt(0)
	v_add_u32_e32 v1, 1, v1
	v_min_u32_e32 v1, v1, v3
	v_cmp_gt_u32_e32 vcc, 4, v1
	s_cbranch_vccz .Lmy_s2_ready
	s_mov_b32 s14, 0

.Lmy_s3_uni:
	s_and_b32 s8, s2, 63
	s_lshl_b32 s9, s8, 2
	s_add_i32 s9, s9, 15200
	v_mov_b32_e32 v0, s9
	v_mov_b32_e32 v1, 1
	global_atomic_add v1, v0, v1, s[52:53] sc0
	v_mov_b32_e32 v2, s9
	v_mov_b32_e32 v3, 4
	s_waitcnt vmcnt(0)
	v_add_u32_e32 v1, 1, v1
	v_min_u32_e32 v1, v1, v3
	v_cmp_gt_u32_e32 vcc, 4, v1
	s_cbranch_vccz .Lmy_s3_ready
	s_mov_b32 s14, 0
